# ret_out: Q chunk staging to LDS pipelined (7 pieces fetched together at constant stride instead of load-wait-write per piece)
# speedup vs baseline: 1.0028x; 1.0028x over previous
.LBB0_738:
	s_ashr_i32 s0, s12, 9
	s_ashr_i32 s1, s0, 31
	s_lshl_b64 s[14:15], s[0:1], 13
	s_lshl_b32 s0, s12, 7
	s_ashr_i32 s13, s12, 31
	s_and_b32 s0, s0, 0x1f80
	s_lshl_b64 s[18:19], s[12:13], 18
	s_bfe_u32 s2, s12, 0x30006
	s_or_b32 s14, s14, s0
	s_add_u32 s0, s4, s18
	s_addc_u32 s1, s5, s19
	s_lshl_b32 s13, s2, 9
	v_readlane_b32 s6, v254, 30
	s_waitcnt vmcnt(0)
	v_ashrrev_i32_e32 v4, 5, v251
	v_readlane_b32 s7, v254, 31
	s_add_u32 s6, s6, s13
	v_lshlrev_b32_e32 v0, 4, v251
	v_ashrrev_i32_e32 v5, 31, v4
	s_addc_u32 s7, s7, 0
	v_and_b32_e32 v2, 0x1f0, v0
	v_mov_b32_e32 v3, v1
	v_lshl_add_u64 v[6:7], s[14:15], 0, v[4:5]
	v_lshl_add_u64 v[38:39], s[6:7], 0, v[2:3]
	v_lshlrev_b64 v[6:7], 12, v[6:7]
	v_lshl_add_u64 v[6:7], v[38:39], 0, v[6:7]
	global_load_dwordx4 v[34:37], v[6:7], off
	v_add_u32_e32 v3, 0x200, v251
	v_and_b32_e32 v6, 0xffffffcf, v251
	v_ashrrev_i32_e32 v40, 5, v3
	v_ashrrev_i32_e32 v7, 31, v6
	v_ashrrev_i32_e32 v41, 31, v40
	v_bfe_u32 v252, v251, 4, 2
	v_lshlrev_b64 v[66:67], 9, v[6:7]
	v_add_u32_e32 v42, 0, v2
	v_lshl_add_u64 v[2:3], s[14:15], 0, v[40:41]
	v_lshlrev_b32_e32 v0, 4, v252
	v_lshlrev_b64 v[46:47], 12, v[2:3]
	v_lshl_add_u64 v[2:3], s[0:1], 0, v[66:67]
	s_movk_i32 s10, 0x210
	v_lshl_add_u64 v[2:3], v[2:3], 0, v[0:1]
	s_movk_i32 s0, 0x2000
	v_mad_u64_u32 v[44:45], s[6:7], v4, s10, v[42:43]
	v_add_co_u32_e32 v4, vcc, s0, v2
	s_movk_i32 s0, 0x4000
	s_nop 0
	v_addc_co_u32_e32 v5, vcc, 0, v3, vcc
	v_add_co_u32_e32 v6, vcc, s0, v2
	v_lshl_add_u64 v[46:47], v[38:39], 0, v[46:47]
	s_nop 0
	v_addc_co_u32_e32 v7, vcc, 0, v3, vcc
	v_add_co_u32_e32 v48, vcc, s75, v2
	v_add_u32_e32 v41, 0x400, v251
	s_nop 0
	v_addc_co_u32_e32 v49, vcc, 0, v3, vcc
	global_load_dwordx4 v[18:21], v[2:3], off
	global_load_dwordx4 v[14:17], v[2:3], off offset:64
	global_load_dwordx4 v[22:25], v[4:5], off
	global_load_dwordx4 v[10:13], v[4:5], off offset:64
	global_load_dwordx4 v[26:29], v[6:7], off
	s_nop 0
	global_load_dwordx4 v[6:9], v[6:7], off offset:64
	s_nop 0
	global_load_dwordx4 v[30:33], v[48:49], off
	global_load_dwordx4 v[2:5], v[48:49], off offset:64
	v_ashrrev_i32_e32 v226, 6, v251
	v_and_b32_e32 v217, 15, v251
	s_movk_i32 s30, 0x210
	s_waitcnt vmcnt(0) lgkmcnt(0)
	ds_write_b128 v44, v[34:37]
	global_load_dwordx4 v[102:105], v[46:47], off
	v_mov_b32_e32 v132, 0x10000
	v_mov_b32_e32 v133, 0
	v_lshl_add_u64 v[130:131], v[46:47], 0, v[132:133]
	global_load_dwordx4 v[106:109], v[130:131], off
	v_lshl_add_u64 v[130:131], v[130:131], 0, v[132:133]
	global_load_dwordx4 v[110:113], v[130:131], off
	v_lshl_add_u64 v[130:131], v[130:131], 0, v[132:133]
	global_load_dwordx4 v[114:117], v[130:131], off
	v_lshl_add_u64 v[130:131], v[130:131], 0, v[132:133]
	global_load_dwordx4 v[118:121], v[130:131], off
	v_lshl_add_u64 v[130:131], v[130:131], 0, v[132:133]
	global_load_dwordx4 v[122:125], v[130:131], off
	v_lshl_add_u64 v[130:131], v[130:131], 0, v[132:133]
	global_load_dwordx4 v[126:129], v[130:131], off
	v_ashrrev_i32_e32 v44, 5, v41
	v_ashrrev_i32_e32 v45, 31, v44
	v_lshl_add_u64 v[46:47], s[14:15], 0, v[44:45]
	v_mad_u64_u32 v[40:41], s[0:1], v40, s10, v[42:43]
	v_lshlrev_b64 v[46:47], 12, v[46:47]
	v_lshl_add_u64 v[46:47], v[38:39], 0, v[46:47]
	v_mad_u64_u32 v[44:45], s[0:1], v44, s10, v[42:43]
	s_waitcnt vmcnt(0) lgkmcnt(0)
	ds_write_b128 v40, v[102:105]
	v_add_u32_e32 v40, 0x600, v251
	v_ashrrev_i32_e32 v40, 5, v40
	v_ashrrev_i32_e32 v41, 31, v40
	v_lshl_add_u64 v[46:47], s[14:15], 0, v[40:41]
	v_lshlrev_b64 v[46:47], 12, v[46:47]
	v_lshl_add_u64 v[46:47], v[38:39], 0, v[46:47]
	v_add_u32_e32 v41, 0x800, v251
	ds_write_b128 v44, v[106:109]
	v_ashrrev_i32_e32 v44, 5, v41
	v_ashrrev_i32_e32 v45, 31, v44
	v_lshl_add_u64 v[46:47], s[14:15], 0, v[44:45]
	v_mad_u64_u32 v[40:41], s[0:1], v40, s10, v[42:43]
	v_lshlrev_b64 v[46:47], 12, v[46:47]
	v_lshl_add_u64 v[46:47], v[38:39], 0, v[46:47]
	v_mad_u64_u32 v[44:45], s[0:1], v44, s10, v[42:43]
	ds_write_b128 v40, v[110:113]
	v_add_u32_e32 v40, 0xa00, v251
	v_ashrrev_i32_e32 v40, 5, v40
	v_ashrrev_i32_e32 v41, 31, v40
	v_lshl_add_u64 v[46:47], s[14:15], 0, v[40:41]
	v_lshlrev_b64 v[46:47], 12, v[46:47]
	v_lshl_add_u64 v[46:47], v[38:39], 0, v[46:47]
	v_add_u32_e32 v41, 0xc00, v251
	ds_write_b128 v44, v[114:117]
	v_ashrrev_i32_e32 v44, 5, v41
	v_ashrrev_i32_e32 v45, 31, v44
	v_lshl_add_u64 v[46:47], s[14:15], 0, v[44:45]
	v_mad_u64_u32 v[40:41], s[0:1], v40, s10, v[42:43]
	v_lshlrev_b64 v[46:47], 12, v[46:47]
	v_lshl_add_u64 v[46:47], v[38:39], 0, v[46:47]
	ds_write_b128 v40, v[118:121]
	v_add_u32_e32 v40, 0xe00, v251
	v_ashrrev_i32_e32 v46, 5, v40
	v_ashrrev_i32_e32 v47, 31, v46
	v_mad_u64_u32 v[40:41], s[0:1], v44, s10, v[42:43]
	v_lshl_add_u64 v[44:45], s[14:15], 0, v[46:47]
	v_lshlrev_b64 v[44:45], 12, v[44:45]
	v_lshl_add_u64 v[38:39], v[38:39], 0, v[44:45]
	v_mad_u64_u32 v[42:43], s[6:7], v46, s10, v[42:43]
	ds_write_b128 v40, v[122:125]
	v_ashrrev_i32_e32 v36, 7, v251
	v_and_b32_e32 v34, 1, v226
	v_lshlrev_b32_e32 v35, 3, v252
	v_cmp_lt_i32_e32 vcc, 1, v36
	v_cmp_eq_u32_e64 s[0:1], 0, v34
	v_lshlrev_b32_e32 v214, 1, v35
	s_or_b64 s[0:1], vcc, s[0:1]
	v_lshl_or_b32 v68, v36, 5, v217
	ds_write_b128 v42, v[126:129]
	s_waitcnt lgkmcnt(0)
	s_barrier
	s_and_saveexec_b64 s[6:7], s[0:1]
	s_xor_b64 s[0:1], exec, s[6:7]
	s_cbranch_execz .LBB0_740
	v_lshlrev_b32_e32 v69, 6, v34
	v_or3_b32 v34, v69, v217, s14
	v_mov_b32_e32 v35, s15
	s_lshl_b32 s2, s2, 8
	v_lshlrev_b64 v[34:35], 12, v[34:35]
	v_lshl_add_u64 v[34:35], s[44:45], 0, v[34:35]
	s_lshl_b32 s54, s2, 1
	v_lshl_add_u64 v[34:35], v[34:35], 0, s[54:55]
	v_mov_b32_e32 v215, v1
	v_lshl_add_u64 v[34:35], v[34:35], 0, v[214:215]
	v_add_co_u32_e32 v166, vcc, s56, v34
	s_nop 1
	v_addc_co_u32_e32 v167, vcc, 0, v35, vcc
	v_add_co_u32_e32 v168, vcc, s57, v34
	s_nop 1
	v_addc_co_u32_e32 v169, vcc, 0, v35, vcc
	v_add_co_u32_e32 v170, vcc, s83, v34
	s_nop 1
	v_addc_co_u32_e32 v171, vcc, 0, v35, vcc
	global_load_dwordx4 v[102:105], v[34:35], off
	global_load_dwordx4 v[106:109], v[34:35], off offset:64
	global_load_dwordx4 v[110:113], v[34:35], off offset:128
	global_load_dwordx4 v[114:117], v[166:167], off
	global_load_dwordx4 v[118:121], v[168:169], off
	global_load_dwordx4 v[122:125], v[170:171], off
	global_load_dwordx4 v[126:129], v[166:167], off offset:64
	global_load_dwordx4 v[130:133], v[168:169], off offset:64
	global_load_dwordx4 v[134:137], v[170:171], off offset:64
	global_load_dwordx4 v[138:141], v[166:167], off offset:128
	global_load_dwordx4 v[142:145], v[34:35], off offset:192
	global_load_dwordx4 v[146:149], v[168:169], off offset:128
	global_load_dwordx4 v[150:153], v[170:171], off offset:128
	global_load_dwordx4 v[154:157], v[166:167], off offset:192
	global_load_dwordx4 v[158:161], v[168:169], off offset:192
	global_load_dwordx4 v[162:165], v[170:171], off offset:192
	global_load_dwordx4 v[174:177], v[34:35], off offset:256
	global_load_dwordx4 v[178:181], v[166:167], off offset:256
	global_load_dwordx4 v[182:185], v[168:169], off offset:256
	global_load_dwordx4 v[186:189], v[170:171], off offset:256
	global_load_dwordx4 v[190:193], v[34:35], off offset:320
	global_load_dwordx4 v[194:197], v[166:167], off offset:320
	global_load_dwordx4 v[198:201], v[168:169], off offset:320
	global_load_dwordx4 v[202:205], v[170:171], off offset:320
	global_load_dwordx4 v[208:211], v[34:35], off offset:384
	global_load_dwordx4 v[230:233], v[166:167], off offset:384
	global_load_dwordx4 v[234:237], v[168:169], off offset:384
	global_load_dwordx4 v[238:241], v[170:171], off offset:384
	global_load_dwordx4 v[242:245], v[34:35], off offset:448
	global_load_dwordx4 v[246:249], v[166:167], off offset:448
	v_lshl_or_b32 v68, v36, 5, v217
	v_mul_lo_u32 v36, v68, s30
	v_add3_u32 v40, 0, v214, v36
	ds_read_b128 v[46:49], v40
	ds_read_b128 v[50:53], v40 offset:8448
	v_add_co_u32_e32 v36, vcc, s56, v34
	v_addc_co_u32_e32 v37, vcc, 0, v35, vcc
	v_add_co_u32_e32 v38, vcc, s57, v34
	ds_read_b128 v[82:85], v40 offset:64
	ds_read_b128 v[90:93], v40 offset:8512
	v_addc_co_u32_e32 v39, vcc, 0, v35, vcc
	s_mov_b32 s54, 0x34000
	s_waitcnt vmcnt(0) lgkmcnt(0)
	v_mov_b32_e32 v42, v102
	v_mov_b32_e32 v43, v103
	v_mov_b32_e32 v44, v104
	v_mov_b32_e32 v45, v105
	v_mov_b32_e32 v78, v106
	v_mov_b32_e32 v79, v107
	v_mov_b32_e32 v80, v108
	v_mov_b32_e32 v81, v109
	v_mov_b32_e32 v94, v110
	v_mov_b32_e32 v95, v111
	v_mov_b32_e32 v96, v112
	v_mov_b32_e32 v97, v113
	s_nop 1
	v_mfma_f32_16x16x32_bf16 v[54:57], v[42:45], v[46:49], 0
	ds_read_b128 v[98:101], v40 offset:8576
	v_mfma_f32_16x16x32_bf16 v[58:61], v[42:45], v[50:53], 0
	s_waitcnt lgkmcnt(0)
	v_mov_b32_e32 v42, v114
	v_mov_b32_e32 v43, v115
	v_mov_b32_e32 v44, v116
	v_mov_b32_e32 v45, v117
	s_nop 1
	v_mfma_f32_16x16x32_bf16 v[62:65], v[42:45], v[46:49], 0
	v_mfma_f32_16x16x32_bf16 v[70:73], v[42:45], v[50:53], 0
	s_waitcnt lgkmcnt(0)
	v_mov_b32_e32 v42, v118
	v_mov_b32_e32 v43, v119
	v_mov_b32_e32 v44, v120
	v_mov_b32_e32 v45, v121
	s_nop 1
	v_mfma_f32_16x16x32_bf16 v[74:77], v[42:45], v[46:49], 0
	v_mfma_f32_16x16x32_bf16 v[86:89], v[42:45], v[50:53], 0
	v_add_co_u32_e32 v42, vcc, s83, v34
	s_nop 1
	v_addc_co_u32_e32 v43, vcc, 0, v35, vcc
	v_mfma_f32_16x16x32_bf16 v[54:57], v[78:81], v[82:85], v[54:57]
	v_mfma_f32_16x16x32_bf16 v[58:61], v[78:81], v[90:93], v[58:61]
	s_waitcnt lgkmcnt(0)
	v_mov_b32_e32 v78, v122
	v_mov_b32_e32 v79, v123
	v_mov_b32_e32 v80, v124
	v_mov_b32_e32 v81, v125
	s_nop 1
	v_mfma_f32_16x16x32_bf16 v[44:47], v[78:81], v[46:49], 0
	v_mfma_f32_16x16x32_bf16 v[48:51], v[78:81], v[50:53], 0
	s_waitcnt lgkmcnt(0)
	v_mov_b32_e32 v78, v126
	v_mov_b32_e32 v79, v127
	v_mov_b32_e32 v80, v128
	v_mov_b32_e32 v81, v129
	s_nop 1
	v_mfma_f32_16x16x32_bf16 v[62:65], v[78:81], v[82:85], v[62:65]
	v_mfma_f32_16x16x32_bf16 v[70:73], v[78:81], v[90:93], v[70:73]
	s_waitcnt lgkmcnt(0)
	v_mov_b32_e32 v78, v130
	v_mov_b32_e32 v79, v131
	v_mov_b32_e32 v80, v132
	v_mov_b32_e32 v81, v133
	s_nop 1
	v_mfma_f32_16x16x32_bf16 v[74:77], v[78:81], v[82:85], v[74:77]
	v_mfma_f32_16x16x32_bf16 v[78:81], v[78:81], v[90:93], v[86:89]
	s_nop 2
	ds_read_b128 v[86:89], v40 offset:128
	s_waitcnt lgkmcnt(0)
	v_mfma_f32_16x16x32_bf16 v[52:55], v[94:97], v[86:89], v[54:57]
	v_mfma_f32_16x16x32_bf16 v[56:59], v[94:97], v[98:101], v[58:61]
	s_waitcnt lgkmcnt(0)
	v_mov_b32_e32 v94, v134
	v_mov_b32_e32 v95, v135
	v_mov_b32_e32 v96, v136
	v_mov_b32_e32 v97, v137
	s_nop 1
	v_mfma_f32_16x16x32_bf16 v[44:47], v[94:97], v[82:85], v[44:47]
	v_mfma_f32_16x16x32_bf16 v[48:51], v[94:97], v[90:93], v[48:51]
	ds_read_b128 v[94:97], v40 offset:8640
	s_waitcnt lgkmcnt(0)
	v_mov_b32_e32 v82, v138
	v_mov_b32_e32 v83, v139
	v_mov_b32_e32 v84, v140
	v_mov_b32_e32 v85, v141
	v_mov_b32_e32 v90, v142
	v_mov_b32_e32 v91, v143
	v_mov_b32_e32 v92, v144
	v_mov_b32_e32 v93, v145
	s_nop 1
	v_mfma_f32_16x16x32_bf16 v[60:63], v[82:85], v[86:89], v[62:65]
	v_mfma_f32_16x16x32_bf16 v[70:73], v[82:85], v[98:101], v[70:73]
	s_waitcnt lgkmcnt(0)
	v_mov_b32_e32 v82, v146
	v_mov_b32_e32 v83, v147
	v_mov_b32_e32 v84, v148
	v_mov_b32_e32 v85, v149
	s_nop 1
	v_mfma_f32_16x16x32_bf16 v[74:77], v[82:85], v[86:89], v[74:77]
	v_mfma_f32_16x16x32_bf16 v[78:81], v[82:85], v[98:101], v[78:81]
	ds_read_b128 v[82:85], v40 offset:192
	s_waitcnt lgkmcnt(0)
	v_mfma_f32_16x16x32_bf16 v[52:55], v[90:93], v[82:85], v[52:55]
	v_mfma_f32_16x16x32_bf16 v[56:59], v[90:93], v[94:97], v[56:59]
	s_waitcnt lgkmcnt(0)
	v_mov_b32_e32 v90, v150
	v_mov_b32_e32 v91, v151
	v_mov_b32_e32 v92, v152
	v_mov_b32_e32 v93, v153
	s_nop 1
	v_mfma_f32_16x16x32_bf16 v[44:47], v[90:93], v[86:89], v[44:47]
	v_mfma_f32_16x16x32_bf16 v[48:51], v[90:93], v[98:101], v[48:51]
	ds_read_b128 v[90:93], v40 offset:8704
	ds_read_b128 v[98:101], v40 offset:8896
	s_waitcnt lgkmcnt(0)
	v_mov_b32_e32 v86, v154
	v_mov_b32_e32 v87, v155
	v_mov_b32_e32 v88, v156
	v_mov_b32_e32 v89, v157
	s_nop 1
	v_mfma_f32_16x16x32_bf16 v[60:63], v[86:89], v[82:85], v[60:63]
	v_mfma_f32_16x16x32_bf16 v[70:73], v[86:89], v[94:97], v[70:73]
	s_waitcnt lgkmcnt(0)
	v_mov_b32_e32 v86, v158
	v_mov_b32_e32 v87, v159
	v_mov_b32_e32 v88, v160
	v_mov_b32_e32 v89, v161
	s_nop 1
	v_mfma_f32_16x16x32_bf16 v[74:77], v[86:89], v[82:85], v[74:77]
	v_mfma_f32_16x16x32_bf16 v[78:81], v[86:89], v[94:97], v[78:81]
	s_waitcnt lgkmcnt(0)
	v_mov_b32_e32 v86, v162
	v_mov_b32_e32 v87, v163
	v_mov_b32_e32 v88, v164
	v_mov_b32_e32 v89, v165
	s_nop 1
	v_mfma_f32_16x16x32_bf16 v[44:47], v[86:89], v[82:85], v[44:47]
	v_mfma_f32_16x16x32_bf16 v[48:51], v[86:89], v[94:97], v[48:51]
	ds_read_b128 v[86:89], v40 offset:256
	s_waitcnt lgkmcnt(0)
	v_mov_b32_e32 v82, v174
	v_mov_b32_e32 v83, v175
	v_mov_b32_e32 v84, v176
	v_mov_b32_e32 v85, v177
	s_nop 1
	v_mfma_f32_16x16x32_bf16 v[52:55], v[82:85], v[86:89], v[52:55]
	v_mfma_f32_16x16x32_bf16 v[56:59], v[82:85], v[90:93], v[56:59]
	s_waitcnt lgkmcnt(0)
	v_mov_b32_e32 v82, v178
	v_mov_b32_e32 v83, v179
	v_mov_b32_e32 v84, v180
	v_mov_b32_e32 v85, v181
	s_nop 1
	v_mfma_f32_16x16x32_bf16 v[60:63], v[82:85], v[86:89], v[60:63]
	v_mfma_f32_16x16x32_bf16 v[70:73], v[82:85], v[90:93], v[70:73]
	s_waitcnt lgkmcnt(0)
	v_mov_b32_e32 v82, v182
	v_mov_b32_e32 v83, v183
	v_mov_b32_e32 v84, v184
	v_mov_b32_e32 v85, v185
	s_nop 1
	v_mfma_f32_16x16x32_bf16 v[74:77], v[82:85], v[86:89], v[74:77]
	v_mfma_f32_16x16x32_bf16 v[78:81], v[82:85], v[90:93], v[78:81]
	s_waitcnt lgkmcnt(0)
	v_mov_b32_e32 v82, v186
	v_mov_b32_e32 v83, v187
	v_mov_b32_e32 v84, v188
	v_mov_b32_e32 v85, v189
	s_nop 1
	v_mfma_f32_16x16x32_bf16 v[44:47], v[82:85], v[86:89], v[44:47]
	v_mfma_f32_16x16x32_bf16 v[48:51], v[82:85], v[90:93], v[48:51]
	ds_read_b128 v[82:85], v40 offset:320
	ds_read_b128 v[90:93], v40 offset:8768
	s_waitcnt lgkmcnt(0)
	v_mov_b32_e32 v86, v190
	v_mov_b32_e32 v87, v191
	v_mov_b32_e32 v88, v192
	v_mov_b32_e32 v89, v193
	s_nop 1
	v_mfma_f32_16x16x32_bf16 v[52:55], v[86:89], v[82:85], v[52:55]
	v_mfma_f32_16x16x32_bf16 v[56:59], v[86:89], v[90:93], v[56:59]
	s_waitcnt lgkmcnt(0)
	v_mov_b32_e32 v86, v194
	v_mov_b32_e32 v87, v195
	v_mov_b32_e32 v88, v196
	v_mov_b32_e32 v89, v197
	s_nop 1
	v_mfma_f32_16x16x32_bf16 v[60:63], v[86:89], v[82:85], v[60:63]
	v_mfma_f32_16x16x32_bf16 v[70:73], v[86:89], v[90:93], v[70:73]
	s_waitcnt lgkmcnt(0)
	v_mov_b32_e32 v86, v198
	v_mov_b32_e32 v87, v199
	v_mov_b32_e32 v88, v200
	v_mov_b32_e32 v89, v201
	s_nop 1
	v_mfma_f32_16x16x32_bf16 v[74:77], v[86:89], v[82:85], v[74:77]
	v_mfma_f32_16x16x32_bf16 v[78:81], v[86:89], v[90:93], v[78:81]
	s_waitcnt lgkmcnt(0)
	v_mov_b32_e32 v86, v202
	v_mov_b32_e32 v87, v203
	v_mov_b32_e32 v88, v204
	v_mov_b32_e32 v89, v205
	s_nop 1
	v_mfma_f32_16x16x32_bf16 v[44:47], v[86:89], v[82:85], v[44:47]
	v_mfma_f32_16x16x32_bf16 v[48:51], v[86:89], v[90:93], v[48:51]
	ds_read_b128 v[86:89], v40 offset:384
	ds_read_b128 v[90:93], v40 offset:8832
	s_waitcnt lgkmcnt(0)
	v_mov_b32_e32 v82, v208
	v_mov_b32_e32 v83, v209
	v_mov_b32_e32 v84, v210
	v_mov_b32_e32 v85, v211
	s_nop 1
	v_mfma_f32_16x16x32_bf16 v[52:55], v[82:85], v[86:89], v[52:55]
	v_mfma_f32_16x16x32_bf16 v[56:59], v[82:85], v[90:93], v[56:59]
	s_waitcnt lgkmcnt(0)
	v_mov_b32_e32 v82, v230
	v_mov_b32_e32 v83, v231
	v_mov_b32_e32 v84, v232
	v_mov_b32_e32 v85, v233
	s_nop 1
	v_mfma_f32_16x16x32_bf16 v[94:97], v[82:85], v[86:89], v[60:63]
	s_nop 2
	s_waitcnt lgkmcnt(0)
	v_mov_b32_e32 v60, v234
	v_mov_b32_e32 v61, v235
	v_mov_b32_e32 v62, v236
	v_mov_b32_e32 v63, v237
	s_nop 1
	v_mfma_f32_16x16x32_bf16 v[74:77], v[60:63], v[86:89], v[74:77]
	v_mfma_f32_16x16x32_bf16 v[78:81], v[60:63], v[90:93], v[78:81]
	v_mfma_f32_16x16x32_bf16 v[70:73], v[82:85], v[90:93], v[70:73]
	s_waitcnt lgkmcnt(0)
	v_mov_b32_e32 v60, v238
	v_mov_b32_e32 v61, v239
	v_mov_b32_e32 v62, v240
	v_mov_b32_e32 v63, v241
	s_nop 1
	v_mfma_f32_16x16x32_bf16 v[82:85], v[60:63], v[86:89], v[44:47]
	s_nop 2
	s_nop 0
	v_mfma_f32_16x16x32_bf16 v[86:89], v[60:63], v[90:93], v[48:51]
	ds_read_b128 v[90:93], v40 offset:448
	s_waitcnt lgkmcnt(0)
	v_mov_b32_e32 v44, v242
	v_mov_b32_e32 v45, v243
	v_mov_b32_e32 v46, v244
	v_mov_b32_e32 v47, v245
	v_mov_b32_e32 v34, v246
	v_mov_b32_e32 v35, v247
	v_mov_b32_e32 v36, v248
	v_mov_b32_e32 v37, v249
	s_nop 1
	v_mfma_f32_16x16x32_bf16 v[62:65], v[44:47], v[90:93], v[52:55]
	v_mfma_f32_16x16x32_bf16 v[58:61], v[44:47], v[98:101], v[56:59]
	v_mfma_f32_16x16x32_bf16 v[54:57], v[34:37], v[90:93], v[94:97]
	v_mfma_f32_16x16x32_bf16 v[50:53], v[34:37], v[98:101], v[70:73]
	global_load_dwordx4 v[102:105], v[168:169], off offset:448
	global_load_dwordx4 v[106:109], v[170:171], off offset:448
	s_waitcnt vmcnt(0) lgkmcnt(0)
	v_mov_b32_e32 v34, v102
	v_mov_b32_e32 v35, v103
	v_mov_b32_e32 v36, v104
	v_mov_b32_e32 v37, v105
	s_nop 1
	v_mfma_f32_16x16x32_bf16 v[46:49], v[34:37], v[90:93], v[74:77]
	v_or_b32_e32 v70, 16, v68
	v_mfma_f32_16x16x32_bf16 v[38:41], v[34:37], v[98:101], v[78:81]
	s_waitcnt lgkmcnt(0)
	v_mov_b32_e32 v34, v106
	v_mov_b32_e32 v35, v107
	v_mov_b32_e32 v36, v108
	v_mov_b32_e32 v37, v109
	s_nop 1
	v_mfma_f32_16x16x32_bf16 v[42:45], v[34:37], v[90:93], v[82:85]
	v_mfma_f32_16x16x32_bf16 v[34:37], v[34:37], v[98:101], v[86:89]
